# P3 loop trimmed: single wait ahead of the QK chain, V piece B DMA through the instruction offset, slot offsets by xor
# speedup vs baseline: 1.0497x; 1.0049x over previous
.LBB0_323:
	s_and_b32 s1, s79, 0x18000
	s_xor_b32 s0, s1, 0x10000
	v_add_u32_e32 v84, s0, v238
	v_add_u32_e32 v85, v84, v230
	v_add_u32_e32 v254, v84, v231
	v_add_u32_e32 v255, v84, v232
	v_add_u32_e32 v84, v84, v233
	ds_read_b128 v[80:83], v85 offset:16384
	ds_read_b128 v[202:205], v254 offset:16384
	ds_read_b128 v[194:197], v255 offset:16384
	ds_read_b128 v[186:189], v84 offset:16384
	ds_read_b128 v[198:201], v85 offset:20480
	ds_read_b128 v[190:193], v254 offset:20480
	ds_read_b128 v[246:249], v255 offset:20480
	ds_read_b128 v[250:253], v84 offset:20480
	s_add_i32 s3, s1, 0x8000
	s_and_b32 s3, s3, 0x18000
	v_add_u32_e32 v158, s3, v235
	ds_read_b64_tr_b16 v[182:183], v158 offset:32768
	ds_read_b64_tr_b16 v[184:185], v158 offset:34816
	ds_read_b64_tr_b16 v[178:179], v158 offset:36864
	ds_read_b64_tr_b16 v[180:181], v158 offset:38912
	s_add_i32 s0, s72, 3
	s_cmp_ge_i32 s0, s33
	s_cbranch_scc1 .LBB0_325
	s_and_b32 s0, s79, 0x18000
	s_add_i32 m0, s0, s94
	s_add_i32 s1, s90, s0
	global_load_lds_dwordx4 v[220:221], off
	s_mov_b32 m0, s1
	s_add_i32 s1, s0, s66
	global_load_lds_dwordx4 v[218:219], off
	s_mov_b32 m0, s1
	v_lshl_add_u64 v[218:219], v[218:219], 0, s[88:89]
	global_load_lds_dwordx4 v[224:225], off
	global_load_lds_dwordx4 v[224:225], off offset:1024
	v_lshl_add_u64 v[220:221], v[220:221], 0, s[88:89]
	v_lshl_add_u64 v[224:225], v[224:225], 0, s[92:93]
.LBB0_325:
	s_waitcnt lgkmcnt(4)
	v_mfma_f32_32x32x16_bf16 v[96:111], v[80:83], v[144:147], v[64:79]
	v_mov_b32_e32 v170, v148
	s_add_i32 s0, s74, s97
	s_sub_i32 s0, s0, 63
	v_mfma_f32_32x32x16_bf16 v[96:111], v[202:205], v[140:143], v[96:111]
	v_cvt_f32_i32_e32 v148, s0
	v_mov_b32_e32 v174, v152
	v_mov_b32_e32 v175, v153
	v_mfma_f32_32x32x16_bf16 v[96:111], v[194:197], v[136:139], v[96:111]
	v_fma_f32 v254, v208, v148, -v207
	v_mov_b32_e32 v176, v154
	v_mov_b32_e32 v177, v155
	v_mfma_f32_32x32x16_bf16 v[96:111], v[186:189], v[132:135], v[96:111]
	v_add_f32_e32 v255, v237, v254
	v_mov_b32_e32 v168, v162
	v_mov_b32_e32 v162, v156
	v_mfma_f32_32x32x16_bf16 v[80:95], v[198:201], v[144:147], v[64:79]
	v_mov_b32_e32 v163, v157
	v_mov_b32_e32 v166, v160
	v_mov_b32_e32 v167, v161
	v_mov_b32_e32 v171, v149
	v_mov_b32_e32 v172, v150
	v_mov_b32_e32 v173, v151
	v_mfma_f32_32x32x16_bf16 v[80:95], v[190:193], v[140:143], v[80:95]
	v_add_f32_e32 v96, v254, v96
	v_exp_f32_e32 v96, v96
	v_add_f32_e32 v97, v254, v97
	v_exp_f32_e32 v97, v97
	v_add_f32_e32 v98, v254, v98
	v_exp_f32_e32 v98, v98
	v_add_f32_e32 v99, v254, v99
	v_exp_f32_e32 v99, v99
	v_add_f32_e32 v100, v254, v100
	v_exp_f32_e32 v100, v100
	v_mfma_f32_32x32x16_bf16 v[80:95], v[246:249], v[136:139], v[80:95]
	v_add_f32_e32 v101, v254, v101
	v_exp_f32_e32 v101, v101
	v_add_f32_e32 v102, v254, v102
	v_exp_f32_e32 v102, v102
	v_add_f32_e32 v103, v254, v103
	v_exp_f32_e32 v103, v103
	v_add_f32_e32 v104, v254, v104
	v_exp_f32_e32 v104, v104
	v_add_f32_e32 v105, v254, v105
	v_exp_f32_e32 v105, v105
	v_mfma_f32_32x32x16_bf16 v[80:95], v[250:253], v[132:135], v[80:95]
	v_add_f32_e32 v106, v254, v106
	v_exp_f32_e32 v106, v106
	v_add_f32_e32 v107, v254, v107
	v_exp_f32_e32 v107, v107
	v_add_f32_e32 v108, v254, v108
	v_exp_f32_e32 v108, v108
	v_add_f32_e32 v109, v254, v109
	v_exp_f32_e32 v109, v109
	v_add_f32_e32 v110, v254, v110
	v_exp_f32_e32 v110, v110
	v_add_f32_e32 v111, v254, v111
	v_exp_f32_e32 v111, v111
	s_cmp_le_i32 s97, s78
	s_cbranch_scc1 .LBB0_327
	v_cmp_gt_i32_e64 s[60:61], 26, v240
	v_cmp_gt_i32_e64 s[62:63], 27, v240
	v_cmp_gt_i32_e64 s[58:59], 25, v240
	s_and_b64 s[60:61], s[62:63], s[60:61]
	v_cmp_gt_i32_e64 s[56:57], 24, v240
	s_and_b64 s[58:59], s[60:61], s[58:59]
	v_cmp_gt_i32_e64 s[54:55], 19, v240
	s_and_b64 s[56:57], s[58:59], s[56:57]
	v_cmp_gt_i32_e64 s[52:53], 18, v240
	s_and_b64 s[54:55], s[56:57], s[54:55]
	v_cmp_gt_i32_e64 s[50:51], 17, v240
	s_and_b64 s[52:53], s[54:55], s[52:53]
	v_cmp_gt_i32_e64 s[48:49], 16, v240
	s_and_b64 s[50:51], s[52:53], s[50:51]
	v_cmp_gt_i32_e64 s[46:47], 11, v240
	s_and_b64 s[48:49], s[50:51], s[48:49]
	v_cmp_gt_i32_e64 s[44:45], 10, v240
	s_and_b64 s[46:47], s[48:49], s[46:47]
	v_cmp_gt_i32_e64 s[42:43], 9, v240
	s_and_b64 s[44:45], s[46:47], s[44:45]
	v_cmp_gt_i32_e64 s[40:41], 8, v240
	s_and_b64 s[42:43], s[44:45], s[42:43]
	v_cmp_gt_i32_e64 s[38:39], 3, v240
	s_and_b64 s[40:41], s[42:43], s[40:41]
	v_cmp_gt_i32_e64 s[36:37], 2, v240
	s_and_b64 s[38:39], s[40:41], s[38:39]
	v_cmp_gt_i32_e64 s[34:35], 1, v240
	s_and_b64 s[36:37], s[38:39], s[36:37]
	v_cmp_gt_i32_e64 s[30:31], 0, v240
	s_and_b64 s[34:35], s[36:37], s[34:35]
	s_and_b64 s[30:31], s[34:35], s[30:31]
	v_cmp_gt_i32_e64 s[28:29], 58, v240
	v_cndmask_b32_e64 v96, v96, v113, s[30:31]
	v_cmp_gt_i32_e64 s[30:31], 59, v240
	v_cmp_gt_i32_e64 s[26:27], 57, v240
	s_and_b64 s[28:29], s[30:31], s[28:29]
	v_cmp_gt_i32_e64 s[24:25], 56, v240
	s_and_b64 s[26:27], s[28:29], s[26:27]
	v_cmp_gt_i32_e64 s[22:23], 51, v240
	s_and_b64 s[24:25], s[26:27], s[24:25]
	v_cmp_gt_i32_e64 s[20:21], 50, v240
	s_and_b64 s[22:23], s[24:25], s[22:23]
	v_cmp_gt_i32_e64 s[18:19], 49, v240
	s_and_b64 s[20:21], s[22:23], s[20:21]
	v_cmp_gt_i32_e64 s[16:17], 48, v240
	s_and_b64 s[18:19], s[20:21], s[18:19]
	v_cmp_gt_i32_e64 s[14:15], 43, v240
	s_and_b64 s[16:17], s[18:19], s[16:17]
	v_cmp_gt_i32_e64 s[12:13], 42, v240
	s_and_b64 s[14:15], s[16:17], s[14:15]
	v_cmp_gt_i32_e64 s[10:11], 41, v240
	s_and_b64 s[12:13], s[14:15], s[12:13]
	v_cmp_gt_i32_e64 s[8:9], 40, v240
	s_and_b64 s[10:11], s[12:13], s[10:11]
	v_cmp_gt_i32_e64 s[6:7], 35, v240
	s_and_b64 s[8:9], s[10:11], s[8:9]
	v_cmp_gt_i32_e64 s[4:5], 34, v240
	s_and_b64 s[6:7], s[8:9], s[6:7]
	v_cmp_gt_i32_e64 s[0:1], 33, v240
	s_and_b64 s[4:5], s[6:7], s[4:5]
	v_cmp_gt_i32_e32 vcc, 32, v240
	s_and_b64 s[0:1], s[4:5], s[0:1]
	s_and_b64 vcc, s[0:1], vcc
	v_cndmask_b32_e64 v111, v111, v113, s[62:63]
	v_cndmask_b32_e64 v110, v110, v113, s[60:61]
	v_cndmask_b32_e64 v109, v109, v113, s[58:59]
	v_cndmask_b32_e64 v108, v108, v113, s[56:57]
	v_cndmask_b32_e64 v107, v107, v113, s[54:55]
	v_cndmask_b32_e64 v106, v106, v113, s[52:53]
	v_cndmask_b32_e64 v105, v105, v113, s[50:51]
	v_cndmask_b32_e64 v104, v104, v113, s[48:49]
	v_cndmask_b32_e64 v103, v103, v113, s[46:47]
	v_cndmask_b32_e64 v102, v102, v113, s[44:45]
	v_cndmask_b32_e64 v101, v101, v113, s[42:43]
	v_cndmask_b32_e64 v100, v100, v113, s[40:41]
	v_cndmask_b32_e64 v99, v99, v113, s[38:39]
	v_cndmask_b32_e64 v98, v98, v113, s[36:37]
	v_cndmask_b32_e64 v97, v97, v113, s[34:35]
	v_cndmask_b32_e64 v95, v95, v228, s[30:31]
	v_cndmask_b32_e64 v94, v94, v228, s[28:29]
	v_cndmask_b32_e64 v93, v93, v228, s[26:27]
	v_cndmask_b32_e64 v92, v92, v228, s[24:25]
	v_cndmask_b32_e64 v91, v91, v228, s[22:23]
	v_cndmask_b32_e64 v90, v90, v228, s[20:21]
	v_cndmask_b32_e64 v89, v89, v228, s[18:19]
	v_cndmask_b32_e64 v88, v88, v228, s[16:17]
	v_cndmask_b32_e64 v87, v87, v228, s[14:15]
	v_cndmask_b32_e64 v86, v86, v228, s[12:13]
	v_cndmask_b32_e64 v85, v85, v228, s[10:11]
	v_cndmask_b32_e64 v84, v84, v228, s[8:9]
	v_cndmask_b32_e64 v83, v83, v228, s[6:7]
	v_cndmask_b32_e64 v82, v82, v228, s[4:5]
	v_cndmask_b32_e64 v81, v81, v228, s[0:1]
	v_cndmask_b32_e32 v80, v80, v228, vcc
